# P6 gate/up epilogue: for 18 of the 32 element pairs of a unit the two scalar (-log2 e)*x multiplies become one packed multiply written into the sigmoid registers, exp/+1/rcp in place (pairs kept only
# baseline (speedup 1.0000x reference)
.LBB0_1613:
	v_and_b32_e32 v130, 63, v0
	v_lshlrev_b32_e32 v130, 2, v130
	v_xor_b32_e32 v131, 0x80, v130
	v_xor_b32_e32 v130, 64, v130
	s_waitcnt vmcnt(8)
	v_add_f32_e32 v228, v228, v229
	v_add_f32_e32 v230, v230, v231
	v_add_f32_e32 v232, v232, v233
	v_add_f32_e32 v234, v234, v235
	v_add_f32_e32 v236, v236, v237
	v_add_f32_e32 v238, v238, v239
	v_add_f32_e32 v240, v240, v241
	v_add_f32_e32 v242, v242, v243
	v_add_f32_e32 v246, v246, v247
	v_add_f32_e32 v248, v248, v249
	v_add_f32_e32 v250, v250, v251
	v_add_f32_e32 v252, v252, v253
	v_add_f32_e32 v228, v228, v230
	v_add_f32_e32 v232, v232, v234
	v_add_f32_e32 v236, v236, v238
	v_add_f32_e32 v240, v240, v242
	v_add_f32_e32 v246, v246, v248
	v_add_f32_e32 v250, v250, v252
	ds_bpermute_b32 v229, v130, v228
	ds_bpermute_b32 v233, v130, v232
	ds_bpermute_b32 v237, v130, v236
	ds_bpermute_b32 v241, v130, v240
	ds_bpermute_b32 v247, v130, v246
	ds_bpermute_b32 v251, v130, v250
	s_waitcnt lgkmcnt(0)
	v_add_f32_e32 v228, v228, v229
	v_add_f32_e32 v232, v232, v233
	v_add_f32_e32 v236, v236, v237
	v_add_f32_e32 v240, v240, v241
	v_add_f32_e32 v246, v246, v247
	v_add_f32_e32 v250, v250, v251
	ds_bpermute_b32 v229, v131, v228
	ds_bpermute_b32 v233, v131, v232
	ds_bpermute_b32 v237, v131, v236
	ds_bpermute_b32 v241, v131, v240
	ds_bpermute_b32 v247, v131, v246
	ds_bpermute_b32 v251, v131, v250
	s_waitcnt lgkmcnt(0)
	v_add_f32_e32 v228, v228, v229
	v_add_f32_e32 v232, v232, v233
	v_add_f32_e32 v236, v236, v237
	v_add_f32_e32 v240, v240, v241
	v_add_f32_e32 v246, v246, v247
	v_add_f32_e32 v250, v250, v251
	v_fmamk_f32 v228, v228, 0x3a800000, v193
	v_fmamk_f32 v232, v232, 0x3a800000, v193
	v_fmamk_f32 v236, v236, 0x3a800000, v193
	v_fmamk_f32 v240, v240, 0x3a800000, v193
	v_fmamk_f32 v246, v246, 0x3a800000, v193
	v_fmamk_f32 v250, v250, 0x3a800000, v193
	v_rsq_f32_e32 v229, v228
	v_rsq_f32_e32 v233, v232
	v_rsq_f32_e32 v237, v236
	v_rsq_f32_e32 v241, v240
	v_rsq_f32_e32 v247, v246
	v_rsq_f32_e32 v251, v250
	s_nop 0
	v_mul_f32_e32 v230, v228, v229
	v_mul_f32_e32 v234, v232, v233
	v_mul_f32_e32 v238, v236, v237
	v_mul_f32_e32 v242, v240, v241
	v_mul_f32_e32 v248, v246, v247
	v_mul_f32_e32 v252, v250, v251
	v_fma_f32 v230, -v230, v229, 1.0
	v_fma_f32 v234, -v234, v233, 1.0
	v_fma_f32 v238, -v238, v237, 1.0
	v_fma_f32 v242, -v242, v241, 1.0
	v_fma_f32 v248, -v248, v247, 1.0
	v_fma_f32 v252, -v252, v251, 1.0
	v_mul_f32_e32 v231, 0.5, v229
	v_mul_f32_e32 v235, 0.5, v233
	v_mul_f32_e32 v239, 0.5, v237
	v_mul_f32_e32 v243, 0.5, v241
	v_mul_f32_e32 v249, 0.5, v247
	v_mul_f32_e32 v253, 0.5, v251
	v_fma_f32 v228, v231, v230, v229
	v_fma_f32 v229, v235, v234, v233
	v_fma_f32 v230, v239, v238, v237
	v_fma_f32 v231, v243, v242, v241
	v_fma_f32 v232, v249, v248, v247
	v_fma_f32 v233, v253, v252, v251
	global_load_dwordx4 v[234:237], v255, s[10:11] offset:2048
	global_load_dwordx4 v[238:241], v255, s[10:11] offset:3072
	v_mov_b32_e32 v254, 0xbfb8aa3b
	v_mov_b32_e32 v242, v130
	v_mov_b32_e32 v243, v131
	v_lshl_add_u32 v178, s6, 8, v1
	v_ashrrev_i32_e32 v179, 31, v178
	s_nop 0
	v_or_b32_e32 v184, 16, v178
	v_or_b32_e32 v182, 32, v178
	v_or_b32_e32 v180, 48, v178
	v_ashrrev_i32_e32 v185, 31, v184
	v_ashrrev_i32_e32 v183, 31, v182
	v_ashrrev_i32_e32 v181, 31, v180
	s_nop 0
	v_lshl_or_b32 v186, s7, 7, v189
	v_ashrrev_i32_e32 v187, 31, v186
	s_nop 0
	s_nop 0
	s_nop 1
	s_nop 0
	s_nop 0
	s_nop 1
	s_nop 1
	s_nop 1
	v_mov_b32_e32 v212, v228
	v_pk_mul_f32 v[126:127], v[126:127], v[212:213] op_sel_hi:[1,0]
	v_pk_mul_f32 v[122:123], v[122:123], v[212:213] op_sel_hi:[1,0]
	v_pk_mul_f32 v[128:129], v[128:129], v[212:213] op_sel_hi:[1,0]
	v_pk_mul_f32 v[118:119], v[118:119], v[212:213] op_sel_hi:[1,0]
	v_pk_mul_f32 v[114:115], v[114:115], v[212:213] op_sel_hi:[1,0]
	v_pk_mul_f32 v[120:121], v[120:121], v[212:213] op_sel_hi:[1,0]
	v_pk_mul_f32 v[124:125], v[124:125], v[212:213] op_sel_hi:[1,0]
	v_mul_f32_e32 v179, 0xbfb8aa3b, v126
	v_mul_f32_e32 v181, 0xbfb8aa3b, v127
	v_pk_mul_f32 v[216:217], v[122:123], v[254:255] op_sel_hi:[1,0]
	s_nop 0
	v_pk_mul_f32 v[218:219], v[128:129], v[254:255] op_sel_hi:[1,0]
	s_nop 0
	v_pk_mul_f32 v[220:221], v[124:125], v[254:255] op_sel_hi:[1,0]
	s_nop 0
	v_exp_f32_e32 v179, v179
	v_exp_f32_e32 v181, v181
	v_exp_f32_e32 v216, v216
	v_exp_f32_e32 v217, v217
	v_exp_f32_e32 v218, v218
	v_exp_f32_e32 v219, v219
	v_exp_f32_e32 v220, v220
	v_exp_f32_e32 v221, v221
	v_add_f32_e32 v179, 1.0, v179
	v_add_f32_e32 v181, 1.0, v181
	v_add_f32_e32 v216, 1.0, v216
	v_add_f32_e32 v217, 1.0, v217
	v_add_f32_e32 v218, 1.0, v218
	v_add_f32_e32 v219, 1.0, v219
	v_add_f32_e32 v220, 1.0, v220
	v_add_f32_e32 v221, 1.0, v221
	v_rcp_f32_e32 v214, v179
	v_rcp_f32_e32 v215, v181
	v_rcp_f32_e32 v216, v216
	v_rcp_f32_e32 v217, v217
	v_rcp_f32_e32 v218, v218
	v_rcp_f32_e32 v219, v219
	v_rcp_f32_e32 v220, v220
	v_rcp_f32_e32 v221, v221
	v_pk_mul_f32 v[126:127], v[126:127], v[214:215]
	v_pk_mul_f32 v[122:123], v[122:123], v[216:217]
	v_pk_mul_f32 v[128:129], v[128:129], v[218:219]
	v_pk_mul_f32 v[118:119], v[118:119], v[126:127]
	v_pk_mul_f32 v[114:115], v[114:115], v[122:123]
	v_pk_mul_f32 v[120:121], v[120:121], v[128:129]
	v_pk_mul_f32 v[122:123], v[124:125], v[220:221]
	v_pk_mul_f32 v[116:117], v[116:117], v[212:213] op_sel_hi:[1,0]
	v_cvt_pk_bf16_f32 v118, v118, v119
	v_pk_mul_f32 v[116:117], v[116:117], v[122:123]
	v_cvt_pk_bf16_f32 v119, v120, v121
	s_nop 0
	s_nop 0
	s_nop 0
	s_nop 1
	v_cvt_pk_bf16_f32 v121, v116, v117
	v_cvt_pk_bf16_f32 v120, v114, v115
	v_mov_b64_e32 v[114:115], s[68:69]
	s_nop 0
	s_nop 1
	s_nop 1
	v_mad_i64_i32 v[122:123], s[6:7], v178, s47, v[114:115]
	v_lshlrev_b64 v[116:117], 1, v[186:187]
	v_mov_b32_e32 v124, v229
	v_pk_mul_f32 v[110:111], v[110:111], v[124:125] op_sel_hi:[1,0]
	v_lshl_add_u64 v[122:123], v[122:123], 0, v[116:117]
	v_mul_f32_e32 v125, 0xbfb8aa3b, v110
	v_mul_f32_e32 v126, 0xbfb8aa3b, v111
	v_exp_f32_e32 v125, v125
	v_exp_f32_e32 v126, v126
	global_store_dwordx4 v[122:123], v[118:121], off
	v_pk_mul_f32 v[106:107], v[106:107], v[124:125] op_sel_hi:[1,0]
	s_nop 0
	v_add_f32_e32 v118, 1.0, v125
	v_add_f32_e32 v119, 1.0, v126
	v_rcp_f32_e32 v118, v118
	v_pk_mul_f32 v[120:121], v[106:107], v[254:255] op_sel_hi:[1,0]
	s_nop 0
	v_rcp_f32_e32 v119, v119
	v_exp_f32_e32 v120, v120
	v_exp_f32_e32 v121, v121
	v_pk_mul_f32 v[102:103], v[102:103], v[124:125] op_sel_hi:[1,0]
	v_pk_mul_f32 v[110:111], v[110:111], v[118:119]
	v_add_f32_e32 v120, 1.0, v120
	v_add_f32_e32 v121, 1.0, v121
	v_pk_mul_f32 v[102:103], v[102:103], v[110:111]
	v_pk_mul_f32 v[110:111], v[112:113], v[124:125] op_sel_hi:[1,0]
	v_rcp_f32_e32 v120, v120
	v_rcp_f32_e32 v121, v121
	v_mul_f32_e32 v112, 0xbfb8aa3b, v110
	v_mul_f32_e32 v113, 0xbfb8aa3b, v111
	v_exp_f32_e32 v112, v112
	v_exp_f32_e32 v113, v113
	v_pk_mul_f32 v[106:107], v[106:107], v[120:121]
	v_pk_mul_f32 v[98:99], v[98:99], v[124:125] op_sel_hi:[1,0]
	v_pk_mul_f32 v[108:109], v[108:109], v[124:125] op_sel_hi:[1,0]
	v_pk_mul_f32 v[106:107], v[98:99], v[106:107]
	v_add_f32_e32 v98, 1.0, v112
	v_add_f32_e32 v99, 1.0, v113
	v_pk_mul_f32 v[112:113], v[108:109], v[254:255] op_sel_hi:[1,0]
	s_nop 0
	v_exp_f32_e32 v112, v112
	v_exp_f32_e32 v113, v113
	v_rcp_f32_e32 v98, v98
	v_rcp_f32_e32 v99, v99
	v_add_f32_e32 v112, 1.0, v112
	v_add_f32_e32 v113, 1.0, v113
	v_rcp_f32_e32 v112, v112
	v_rcp_f32_e32 v113, v113
	v_pk_mul_f32 v[98:99], v[110:111], v[98:99]
	v_pk_mul_f32 v[104:105], v[104:105], v[124:125] op_sel_hi:[1,0]
	v_pk_mul_f32 v[100:101], v[100:101], v[124:125] op_sel_hi:[1,0]
	v_pk_mul_f32 v[104:105], v[104:105], v[98:99]
	v_pk_mul_f32 v[98:99], v[108:109], v[112:113]
	v_pk_mul_f32 v[108:109], v[100:101], v[98:99]
	v_cvt_pk_bf16_f32 v98, v102, v103
	s_nop 0
	s_nop 0
	s_nop 0
	v_cvt_pk_bf16_f32 v101, v108, v109
	s_nop 0
	v_cvt_pk_bf16_f32 v99, v104, v105
	v_cvt_pk_bf16_f32 v100, v106, v107
	s_nop 0
	s_nop 1
	s_nop 1
	v_mad_i64_i32 v[102:103], s[6:7], v184, s47, v[114:115]
	v_lshl_add_u64 v[102:103], v[102:103], 0, v[116:117]
	v_mov_b32_e32 v104, v230
	v_pk_mul_f32 v[94:95], v[94:95], v[104:105] op_sel_hi:[1,0]
	global_store_dwordx4 v[102:103], v[98:101], off
	v_mul_f32_e32 v105, 0xbfb8aa3b, v94
	v_mul_f32_e32 v106, 0xbfb8aa3b, v95
	v_exp_f32_e32 v105, v105
	v_exp_f32_e32 v106, v106
	v_add_u32_e32 v102, 0x90, v178
	v_ashrrev_i32_e32 v103, 31, v102
	v_add_f32_e32 v98, 1.0, v105
	v_add_f32_e32 v99, 1.0, v106
	v_pk_mul_f32 v[90:91], v[90:91], v[104:105] op_sel_hi:[1,0]
	v_rcp_f32_e32 v98, v98
	v_pk_mul_f32 v[100:101], v[90:91], v[254:255] op_sel_hi:[1,0]
	s_nop 0
	v_rcp_f32_e32 v99, v99
	v_exp_f32_e32 v100, v100
	v_exp_f32_e32 v101, v101
	v_pk_mul_f32 v[86:87], v[86:87], v[104:105] op_sel_hi:[1,0]
	v_pk_mul_f32 v[94:95], v[94:95], v[98:99]
	v_add_f32_e32 v100, 1.0, v100
	v_add_f32_e32 v101, 1.0, v101
	v_pk_mul_f32 v[86:87], v[86:87], v[94:95]
	v_pk_mul_f32 v[94:95], v[96:97], v[104:105] op_sel_hi:[1,0]
	v_rcp_f32_e32 v100, v100
	v_rcp_f32_e32 v101, v101
	v_mul_f32_e32 v96, 0xbfb8aa3b, v94
	v_mul_f32_e32 v97, 0xbfb8aa3b, v95
	v_exp_f32_e32 v96, v96
	v_exp_f32_e32 v97, v97
	v_pk_mul_f32 v[90:91], v[90:91], v[100:101]
	v_pk_mul_f32 v[82:83], v[82:83], v[104:105] op_sel_hi:[1,0]
	v_pk_mul_f32 v[92:93], v[92:93], v[104:105] op_sel_hi:[1,0]
	v_pk_mul_f32 v[90:91], v[82:83], v[90:91]
	v_add_f32_e32 v82, 1.0, v96
	v_add_f32_e32 v83, 1.0, v97
	v_pk_mul_f32 v[96:97], v[92:93], v[254:255] op_sel_hi:[1,0]
	s_nop 0
	v_exp_f32_e32 v96, v96
	v_exp_f32_e32 v97, v97
	v_rcp_f32_e32 v82, v82
	v_rcp_f32_e32 v83, v83
	v_add_f32_e32 v96, 1.0, v96
	v_add_f32_e32 v97, 1.0, v97
	v_rcp_f32_e32 v96, v96
	v_rcp_f32_e32 v97, v97
	v_pk_mul_f32 v[82:83], v[94:95], v[82:83]
	v_pk_mul_f32 v[88:89], v[88:89], v[104:105] op_sel_hi:[1,0]
	v_pk_mul_f32 v[84:85], v[84:85], v[104:105] op_sel_hi:[1,0]
	v_pk_mul_f32 v[88:89], v[88:89], v[82:83]
	v_pk_mul_f32 v[82:83], v[92:93], v[96:97]
	v_pk_mul_f32 v[92:93], v[84:85], v[82:83]
	v_cvt_pk_bf16_f32 v82, v86, v87
	v_add_u32_e32 v104, 0x80, v178
	v_ashrrev_i32_e32 v105, 31, v104
	v_add_u32_e32 v100, 0xa0, v178
	v_cvt_pk_bf16_f32 v85, v92, v93
	v_ashrrev_i32_e32 v101, 31, v100
	v_cvt_pk_bf16_f32 v83, v88, v89
	v_cvt_pk_bf16_f32 v84, v90, v91
	s_nop 0
	s_nop 1
	s_nop 1
	v_mad_i64_i32 v[86:87], s[6:7], v182, s47, v[114:115]
	v_lshl_add_u64 v[86:87], v[86:87], 0, v[116:117]
	v_mov_b32_e32 v88, v231
	v_pk_mul_f32 v[78:79], v[78:79], v[88:89] op_sel_hi:[1,0]
	global_store_dwordx4 v[86:87], v[82:85], off
	v_mul_f32_e32 v89, 0xbfb8aa3b, v78
	v_mul_f32_e32 v90, 0xbfb8aa3b, v79
	v_exp_f32_e32 v89, v89
	v_exp_f32_e32 v90, v90
	v_add_f32_e32 v82, 1.0, v89
	v_add_f32_e32 v83, 1.0, v90
	v_pk_mul_f32 v[74:75], v[74:75], v[88:89] op_sel_hi:[1,0]
	v_rcp_f32_e32 v82, v82
	v_pk_mul_f32 v[84:85], v[74:75], v[254:255] op_sel_hi:[1,0]
	s_nop 0
	v_rcp_f32_e32 v83, v83
	v_exp_f32_e32 v84, v84
	v_exp_f32_e32 v85, v85
	v_pk_mul_f32 v[70:71], v[70:71], v[88:89] op_sel_hi:[1,0]
	v_pk_mul_f32 v[78:79], v[78:79], v[82:83]
	v_add_f32_e32 v84, 1.0, v84
	v_add_f32_e32 v85, 1.0, v85
	v_pk_mul_f32 v[70:71], v[70:71], v[78:79]
	v_pk_mul_f32 v[78:79], v[80:81], v[88:89] op_sel_hi:[1,0]
	v_rcp_f32_e32 v84, v84
	v_rcp_f32_e32 v85, v85
	v_mul_f32_e32 v80, 0xbfb8aa3b, v78
	v_mul_f32_e32 v81, 0xbfb8aa3b, v79
	v_exp_f32_e32 v80, v80
	v_exp_f32_e32 v81, v81
	v_pk_mul_f32 v[74:75], v[74:75], v[84:85]
	v_pk_mul_f32 v[66:67], v[66:67], v[88:89] op_sel_hi:[1,0]
	v_pk_mul_f32 v[76:77], v[76:77], v[88:89] op_sel_hi:[1,0]
	v_pk_mul_f32 v[74:75], v[66:67], v[74:75]
	v_add_f32_e32 v66, 1.0, v80
	v_add_f32_e32 v67, 1.0, v81
	v_pk_mul_f32 v[80:81], v[76:77], v[254:255] op_sel_hi:[1,0]
	s_nop 0
	v_exp_f32_e32 v80, v80
	v_exp_f32_e32 v81, v81
	v_rcp_f32_e32 v66, v66
	v_rcp_f32_e32 v67, v67
	v_add_f32_e32 v80, 1.0, v80
	v_add_f32_e32 v81, 1.0, v81
	v_rcp_f32_e32 v80, v80
	v_rcp_f32_e32 v81, v81
	v_pk_mul_f32 v[66:67], v[78:79], v[66:67]
	v_pk_mul_f32 v[72:73], v[72:73], v[88:89] op_sel_hi:[1,0]
	v_pk_mul_f32 v[68:69], v[68:69], v[88:89] op_sel_hi:[1,0]
	v_pk_mul_f32 v[72:73], v[72:73], v[66:67]
	v_pk_mul_f32 v[66:67], v[76:77], v[80:81]
	v_pk_mul_f32 v[76:77], v[68:69], v[66:67]
	v_cvt_pk_bf16_f32 v66, v70, v71
	v_mad_i64_i32 v[70:71], s[6:7], v180, s47, v[114:115]
	v_cvt_pk_bf16_f32 v67, v72, v73
	v_cvt_pk_bf16_f32 v68, v74, v75
	v_cvt_pk_bf16_f32 v69, v76, v77
	v_lshl_add_u64 v[70:71], v[70:71], 0, v[116:117]
	global_store_dwordx4 v[70:71], v[66:69], off
	s_nop 0
	s_nop 0
	s_nop 0
	s_nop 0
	v_add_u32_e32 v98, 0xb0, v178
	v_ashrrev_i32_e32 v99, 31, v98
	s_nop 0
	s_nop 1
	s_nop 0
	s_nop 1
	s_nop 1
	v_mov_b32_e32 v126, v232
	v_pk_mul_f32 v[62:63], v[62:63], v[126:127] op_sel_hi:[1,0]
	v_pk_mul_f32 v[58:59], v[58:59], v[126:127] op_sel_hi:[1,0]
	v_pk_mul_f32 v[128:129], v[62:63], v[254:255] op_sel_hi:[1,0]
	v_exp_f32_e32 v128, v128
	s_nop 0
	v_exp_f32_e32 v129, v129
	v_pk_mul_f32 v[130:131], v[58:59], v[254:255] op_sel_hi:[1,0]
	v_add_f32_e32 v128, 1.0, v128
	v_rcp_f32_e32 v128, v128
	v_add_f32_e32 v129, 1.0, v129
	s_nop 0
	v_exp_f32_e32 v130, v130
	v_rcp_f32_e32 v129, v129
	v_exp_f32_e32 v131, v131
	v_pk_mul_f32 v[54:55], v[54:55], v[126:127] op_sel_hi:[1,0]
	v_add_f32_e32 v130, 1.0, v130
	v_pk_mul_f32 v[62:63], v[62:63], v[128:129]
	v_rcp_f32_e32 v130, v130
	v_add_f32_e32 v131, 1.0, v131
	v_pk_mul_f32 v[54:55], v[54:55], v[62:63]
	v_pk_mul_f32 v[62:63], v[64:65], v[126:127] op_sel_hi:[1,0]
	v_rcp_f32_e32 v131, v131
	v_mul_f32_e32 v64, 0xbfb8aa3b, v62
	v_mul_f32_e32 v65, 0xbfb8aa3b, v63
	v_exp_f32_e32 v64, v64
	v_exp_f32_e32 v65, v65
	v_pk_mul_f32 v[58:59], v[58:59], v[130:131]
	v_pk_mul_f32 v[50:51], v[50:51], v[126:127] op_sel_hi:[1,0]
	v_pk_mul_f32 v[60:61], v[60:61], v[126:127] op_sel_hi:[1,0]
	v_pk_mul_f32 v[58:59], v[50:51], v[58:59]
	v_add_f32_e32 v50, 1.0, v64
	v_add_f32_e32 v51, 1.0, v65
	v_pk_mul_f32 v[64:65], v[60:61], v[254:255] op_sel_hi:[1,0]
	s_nop 0
	v_exp_f32_e32 v64, v64
	v_exp_f32_e32 v65, v65
	v_rcp_f32_e32 v50, v50
	v_rcp_f32_e32 v51, v51
	v_add_f32_e32 v64, 1.0, v64
	v_add_f32_e32 v65, 1.0, v65
	v_rcp_f32_e32 v64, v64
	v_rcp_f32_e32 v65, v65
	v_pk_mul_f32 v[50:51], v[62:63], v[50:51]
	v_pk_mul_f32 v[56:57], v[56:57], v[126:127] op_sel_hi:[1,0]
	v_pk_mul_f32 v[52:53], v[52:53], v[126:127] op_sel_hi:[1,0]
	v_pk_mul_f32 v[56:57], v[56:57], v[50:51]
	v_pk_mul_f32 v[50:51], v[60:61], v[64:65]
	v_pk_mul_f32 v[60:61], v[52:53], v[50:51]
	v_cvt_pk_bf16_f32 v50, v54, v55
	s_nop 0
	s_nop 0
	s_nop 0
	v_cvt_pk_bf16_f32 v53, v60, v61
	s_nop 0
	v_cvt_pk_bf16_f32 v51, v56, v57
	v_cvt_pk_bf16_f32 v52, v58, v59
	s_nop 0
	s_nop 1
	s_nop 1
	v_mad_i64_i32 v[54:55], s[6:7], v104, s47, v[114:115]
	v_lshl_add_u64 v[54:55], v[54:55], 0, v[116:117]
	v_mov_b32_e32 v56, v233
	v_pk_mul_f32 v[46:47], v[46:47], v[56:57] op_sel_hi:[1,0]
	global_store_dwordx4 v[54:55], v[50:53], off
	v_mul_f32_e32 v57, 0xbfb8aa3b, v46
	v_mul_f32_e32 v58, 0xbfb8aa3b, v47
	v_exp_f32_e32 v57, v57
	v_exp_f32_e32 v58, v58
	v_add_f32_e32 v50, 1.0, v57
	v_add_f32_e32 v51, 1.0, v58
	v_pk_mul_f32 v[42:43], v[42:43], v[56:57] op_sel_hi:[1,0]
	v_rcp_f32_e32 v50, v50
	v_pk_mul_f32 v[52:53], v[42:43], v[254:255] op_sel_hi:[1,0]
	s_nop 0
	v_rcp_f32_e32 v51, v51
	v_exp_f32_e32 v52, v52
	v_exp_f32_e32 v53, v53
	v_pk_mul_f32 v[38:39], v[38:39], v[56:57] op_sel_hi:[1,0]
	v_pk_mul_f32 v[46:47], v[46:47], v[50:51]
	v_add_f32_e32 v52, 1.0, v52
	v_add_f32_e32 v53, 1.0, v53
	v_pk_mul_f32 v[38:39], v[38:39], v[46:47]
	v_pk_mul_f32 v[46:47], v[48:49], v[56:57] op_sel_hi:[1,0]
	v_rcp_f32_e32 v52, v52
	v_rcp_f32_e32 v53, v53
	v_mul_f32_e32 v48, 0xbfb8aa3b, v46
	v_mul_f32_e32 v49, 0xbfb8aa3b, v47
	v_exp_f32_e32 v48, v48
	v_exp_f32_e32 v49, v49
	v_pk_mul_f32 v[42:43], v[42:43], v[52:53]
	v_pk_mul_f32 v[34:35], v[34:35], v[56:57] op_sel_hi:[1,0]
	v_pk_mul_f32 v[44:45], v[44:45], v[56:57] op_sel_hi:[1,0]
	v_pk_mul_f32 v[42:43], v[34:35], v[42:43]
	v_add_f32_e32 v34, 1.0, v48
	v_add_f32_e32 v35, 1.0, v49
	v_pk_mul_f32 v[48:49], v[44:45], v[254:255] op_sel_hi:[1,0]
	s_nop 0
	v_exp_f32_e32 v48, v48
	v_exp_f32_e32 v49, v49
	v_rcp_f32_e32 v34, v34
	v_rcp_f32_e32 v35, v35
	v_add_f32_e32 v48, 1.0, v48
	v_add_f32_e32 v49, 1.0, v49
	v_rcp_f32_e32 v48, v48
	v_rcp_f32_e32 v49, v49
	v_pk_mul_f32 v[34:35], v[46:47], v[34:35]
	v_pk_mul_f32 v[40:41], v[40:41], v[56:57] op_sel_hi:[1,0]
	v_pk_mul_f32 v[36:37], v[36:37], v[56:57] op_sel_hi:[1,0]
	v_pk_mul_f32 v[40:41], v[40:41], v[34:35]
	v_pk_mul_f32 v[34:35], v[44:45], v[48:49]
	v_pk_mul_f32 v[44:45], v[36:37], v[34:35]
	v_cvt_pk_bf16_f32 v34, v38, v39
	s_nop 0
	s_nop 0
	s_nop 0
	v_cvt_pk_bf16_f32 v37, v44, v45
	s_nop 0
	v_cvt_pk_bf16_f32 v35, v40, v41
	v_cvt_pk_bf16_f32 v36, v42, v43
	s_nop 0
	s_nop 1
	s_nop 1
	v_mad_i64_i32 v[38:39], s[6:7], v102, s47, v[114:115]
	v_lshl_add_u64 v[38:39], v[38:39], 0, v[116:117]
	s_waitcnt vmcnt(5)
	v_add_f32_e32 v234, v234, v235
	v_add_f32_e32 v236, v236, v237
	v_add_f32_e32 v238, v238, v239
	v_add_f32_e32 v240, v240, v241
	v_add_f32_e32 v234, v234, v236
	v_add_f32_e32 v238, v238, v240
	ds_bpermute_b32 v235, v242, v234
	ds_bpermute_b32 v239, v242, v238
	s_waitcnt lgkmcnt(0)
	v_add_f32_e32 v234, v234, v235
	v_add_f32_e32 v238, v238, v239
	ds_bpermute_b32 v235, v243, v234
	ds_bpermute_b32 v239, v243, v238
	s_waitcnt lgkmcnt(0)
	v_add_f32_e32 v234, v234, v235
	v_add_f32_e32 v238, v238, v239
	v_fmamk_f32 v234, v234, 0x3a800000, v193
	v_fmamk_f32 v238, v238, 0x3a800000, v193
	v_rsq_f32_e32 v235, v234
	v_rsq_f32_e32 v239, v238
	s_nop 0
	v_mul_f32_e32 v236, v234, v235
	v_mul_f32_e32 v240, v238, v239
	v_fma_f32 v236, -v236, v235, 1.0
	v_fma_f32 v240, -v240, v239, 1.0
	v_mul_f32_e32 v237, 0.5, v235
	v_mul_f32_e32 v241, 0.5, v239
	v_fma_f32 v246, v237, v236, v235
	v_fma_f32 v247, v241, v240, v239
	v_mov_b32_e32 v40, v246
	v_pk_mul_f32 v[30:31], v[30:31], v[40:41] op_sel_hi:[1,0]
	global_store_dwordx4 v[38:39], v[34:37], off
	v_mul_f32_e32 v41, 0xbfb8aa3b, v30
	v_mul_f32_e32 v42, 0xbfb8aa3b, v31
	v_exp_f32_e32 v41, v41
	v_exp_f32_e32 v42, v42
	v_add_f32_e32 v34, 1.0, v41
	v_add_f32_e32 v35, 1.0, v42
	v_pk_mul_f32 v[26:27], v[26:27], v[40:41] op_sel_hi:[1,0]
	v_rcp_f32_e32 v34, v34
	v_pk_mul_f32 v[36:37], v[26:27], v[254:255] op_sel_hi:[1,0]
	s_nop 0
	v_rcp_f32_e32 v35, v35
	v_exp_f32_e32 v36, v36
	v_exp_f32_e32 v37, v37
	v_pk_mul_f32 v[22:23], v[22:23], v[40:41] op_sel_hi:[1,0]
	v_pk_mul_f32 v[30:31], v[30:31], v[34:35]
	v_add_f32_e32 v36, 1.0, v36
	v_add_f32_e32 v37, 1.0, v37
	v_pk_mul_f32 v[22:23], v[22:23], v[30:31]
	v_pk_mul_f32 v[30:31], v[32:33], v[40:41] op_sel_hi:[1,0]
	v_rcp_f32_e32 v36, v36
	v_rcp_f32_e32 v37, v37
	v_mul_f32_e32 v32, 0xbfb8aa3b, v30
	v_mul_f32_e32 v33, 0xbfb8aa3b, v31
	v_exp_f32_e32 v32, v32
	v_exp_f32_e32 v33, v33
	v_pk_mul_f32 v[26:27], v[26:27], v[36:37]
	v_pk_mul_f32 v[18:19], v[18:19], v[40:41] op_sel_hi:[1,0]
	v_pk_mul_f32 v[28:29], v[28:29], v[40:41] op_sel_hi:[1,0]
	v_pk_mul_f32 v[26:27], v[18:19], v[26:27]
	v_add_f32_e32 v18, 1.0, v32
	v_add_f32_e32 v19, 1.0, v33
	v_pk_mul_f32 v[32:33], v[28:29], v[254:255] op_sel_hi:[1,0]
	s_nop 0
	v_exp_f32_e32 v32, v32
	v_exp_f32_e32 v33, v33
	v_rcp_f32_e32 v18, v18
	v_rcp_f32_e32 v19, v19
	v_add_f32_e32 v32, 1.0, v32
	v_add_f32_e32 v33, 1.0, v33
	v_rcp_f32_e32 v32, v32
	v_rcp_f32_e32 v33, v33
	v_pk_mul_f32 v[18:19], v[30:31], v[18:19]
	v_pk_mul_f32 v[24:25], v[24:25], v[40:41] op_sel_hi:[1,0]
	v_pk_mul_f32 v[20:21], v[20:21], v[40:41] op_sel_hi:[1,0]
	v_pk_mul_f32 v[24:25], v[24:25], v[18:19]
	v_pk_mul_f32 v[18:19], v[28:29], v[32:33]
	v_pk_mul_f32 v[28:29], v[20:21], v[18:19]
	v_cvt_pk_bf16_f32 v18, v22, v23
	s_nop 0
	s_nop 0
	s_nop 0
	v_cvt_pk_bf16_f32 v21, v28, v29
	s_nop 0
	v_cvt_pk_bf16_f32 v19, v24, v25
	v_cvt_pk_bf16_f32 v20, v26, v27
	s_nop 0
	s_nop 1
	s_nop 1
	v_mad_i64_i32 v[22:23], s[6:7], v100, s47, v[114:115]
	v_lshl_add_u64 v[22:23], v[22:23], 0, v[116:117]
	v_mov_b32_e32 v24, v247
	v_pk_mul_f32 v[14:15], v[14:15], v[24:25] op_sel_hi:[1,0]
	global_store_dwordx4 v[22:23], v[18:21], off
	v_mul_f32_e32 v25, 0xbfb8aa3b, v14
	v_mul_f32_e32 v26, 0xbfb8aa3b, v15
	v_exp_f32_e32 v25, v25
	v_exp_f32_e32 v26, v26
	s_andn2_b64 vcc, exec, s[4:5]
	s_mov_b64 s[4:5], -1
	v_add_f32_e32 v18, 1.0, v25
	v_add_f32_e32 v19, 1.0, v26
	v_pk_mul_f32 v[10:11], v[10:11], v[24:25] op_sel_hi:[1,0]
	v_rcp_f32_e32 v18, v18
	v_pk_mul_f32 v[20:21], v[10:11], v[254:255] op_sel_hi:[1,0]
	s_nop 0
	v_rcp_f32_e32 v19, v19
	v_exp_f32_e32 v20, v20
	v_exp_f32_e32 v21, v21
	v_pk_mul_f32 v[6:7], v[6:7], v[24:25] op_sel_hi:[1,0]
	v_pk_mul_f32 v[14:15], v[14:15], v[18:19]
	v_add_f32_e32 v20, 1.0, v20
	v_add_f32_e32 v21, 1.0, v21
	v_pk_mul_f32 v[6:7], v[6:7], v[14:15]
	v_pk_mul_f32 v[14:15], v[16:17], v[24:25] op_sel_hi:[1,0]
	v_rcp_f32_e32 v20, v20
	v_rcp_f32_e32 v21, v21
	v_mul_f32_e32 v16, 0xbfb8aa3b, v14
	v_mul_f32_e32 v17, 0xbfb8aa3b, v15
	v_exp_f32_e32 v16, v16
	v_exp_f32_e32 v17, v17
	v_pk_mul_f32 v[10:11], v[10:11], v[20:21]
	v_pk_mul_f32 v[2:3], v[2:3], v[24:25] op_sel_hi:[1,0]
	v_pk_mul_f32 v[12:13], v[12:13], v[24:25] op_sel_hi:[1,0]
	v_pk_mul_f32 v[10:11], v[2:3], v[10:11]
	v_add_f32_e32 v2, 1.0, v16
	v_add_f32_e32 v3, 1.0, v17
	v_pk_mul_f32 v[16:17], v[12:13], v[254:255] op_sel_hi:[1,0]
	s_nop 0
	v_exp_f32_e32 v16, v16
	v_exp_f32_e32 v17, v17
	v_rcp_f32_e32 v2, v2
	v_rcp_f32_e32 v3, v3
	v_add_f32_e32 v16, 1.0, v16
	v_add_f32_e32 v17, 1.0, v17
	v_rcp_f32_e32 v16, v16
	v_rcp_f32_e32 v17, v17
	v_pk_mul_f32 v[2:3], v[14:15], v[2:3]
	v_pk_mul_f32 v[8:9], v[8:9], v[24:25] op_sel_hi:[1,0]
	v_pk_mul_f32 v[4:5], v[4:5], v[24:25] op_sel_hi:[1,0]
	v_pk_mul_f32 v[8:9], v[8:9], v[2:3]
	v_pk_mul_f32 v[2:3], v[12:13], v[16:17]
	s_nop 0
	v_pk_mul_f32 v[12:13], v[4:5], v[2:3]
	v_cvt_pk_bf16_f32 v2, v6, v7
	v_mad_i64_i32 v[6:7], s[6:7], v98, s47, v[114:115]
	v_cvt_pk_bf16_f32 v3, v8, v9
	v_cvt_pk_bf16_f32 v4, v10, v11
	v_cvt_pk_bf16_f32 v5, v12, v13
	v_lshl_add_u64 v[6:7], v[6:7], 0, v[116:117]
	global_store_dwordx4 v[6:7], v[2:5], off
	s_cbranch_vccnz .LBB0_1606
	s_andn2_b64 vcc, exec, s[8:9]
	s_cbranch_vccnz .LBB0_1605
	s_barrier
	s_branch .LBB0_1605
